# attention first-half end: step barrier and the next K-fragment LDS reads hoisted above the 16 exps so the read latency overlaps them, bit-identical
# baseline (speedup 1.0000x reference)
; #define SBAR() __builtin_amdgcn_sched_barrier(0)
; #define SLOAD(i, k0) do { sr_[i].vs0 = *reinterpret_cast<const bf16x8*>(&Vh[(size_t)((k0) + sr) * 128 + sc]); sr_[i].vs1 = *reinterpret_cast<const bf16x8*>(&Vh[(size_t)((k0) + 32 + sr) * 128 + sc]); \
;     sr_[i].ks0 = *reinterpret_cast<const bf16x8*>(&Kh[(size_t)((k0) + kr) * 64 + kc]); } while (0)
; #define SWRITE(b, i) do { *(bf16x8*)(V_lds + (b) * AT_SHM_V + vst0) = sr_[i].vs0; *(bf16x8*)(V_lds + (b) * AT_SHM_V + vst1) = sr_[i].vs1; \
;     *(bf16x8*)(K_lds + (b) * AT_SHM_K + kst) = sr_[i].ks0; } while (0)
; #define SWAIT() asm volatile("s_waitcnt vmcnt(3)" ::: "memory")
; DEV void partialSM(f32x16& p0, f32x16& p1, float& m_reg, float& mn, float& alpha) {
;     ...
;   for (int r = 0; r < 16; ++r) p0[r] = __builtin_amdgcn_exp2f(p0[r]);
; }
; DEV void finishSM(f32x16& p0, f32x16& p1, float alpha, float& l_reg, bf16x8& pa0, bf16x8& pa1, bf16x8& pa2, bf16x8& pa3) {
; #pragma unroll
;   for (int r = 0; r < 16; ++r) p1[r] = __builtin_amdgcn_exp2f(p1[r]);
;   float ps = 0;
; #pragma unroll
;   for (int r = 0; r < 16; ++r) ps += p0[r];
; #pragma unroll
;   for (int r = 0; r < 16; ++r) ps += p1[r];
;   { auto rr = __builtin_amdgcn_permlane32_swap(__float_as_uint(ps), __float_as_uint(ps), false, false);
;     ps = __uint_as_float(rr[0]) + __uint_as_float(rr[1]); }
;   l_reg = l_reg * alpha + ps;
;     ...
;   PK4(p0, 0, pa0); PK4(p0, 8, pa1); PK4(p1, 0, pa2); PK4(p1, 8, pa3);
; DEV void attn_pass(const u16* __restrict__ Qb, const u16* __restrict__ Kh, const u16* __restrict__ Vh, int seq, f32x16* o, float* rli) {
;     ...
;     SBAR(); qkt(pB0, pB1, K_lds + b0 * AT_SHM_K, qr, r32, hi);
;     finishSM(pA0, pA1, alA, l_reg, pa0, pa1, pa2, pa3); SBAR();
;     SLOAD(SO, (j + 2) * 64); SBAR();
;     pv_d0(o, vb0 + bm1 * AT_SHM_V, pa0, pa1, pa2, pa3); partialSM(pB0, pB1, m_reg, mnB, alB);
;     SWAIT(); SWRITE(b1, SE);
;     RESC(alB); __syncthreads();
;     SBAR(); qkt(pA0, pA1, K_lds + b1 * AT_SHM_K, qr, r32, hi);
;     finishSM(pB0, pB1, alB, l_reg, pa0, pa1, pa2, pa3); SBAR();
;     if (j + 3 < NT) SLOAD(SE, (j + 3) * 64); SBAR();
;     pv_d0(o, vb0 + b0 * AT_SHM_V, pa0, pa1, pa2, pa3); partialSM(pA0, pA1, m_reg, mnA, alA);
.LBB0_74:
	v_subrev_u32_e32 v137, s15, v183
	v_subrev_u32_e32 v138, s15, v185
	v_subrev_u32_e32 v146, s15, v199
	v_subrev_u32_e32 v147, s15, v201
	v_mov_b32_e32 v149, v64
	v_mov_b32_e32 v150, v65
	v_mov_b32_e32 v151, v66
	v_mov_b32_e32 v164, v67
	v_mov_b32_e32 v165, v68
	v_mov_b32_e32 v166, v69
	v_mov_b32_e32 v167, v70
	v_mov_b32_e32 v186, v71
	v_mov_b32_e32 v187, v72
	v_mov_b32_e32 v188, v73
	v_mov_b32_e32 v189, v74
	v_mov_b32_e32 v190, v75
	v_mov_b32_e32 v191, v76
	v_mov_b32_e32 v192, v77
	v_mov_b32_e32 v193, v78
	v_mov_b32_e32 v148, v79
	s_waitcnt lgkmcnt(0)
	s_barrier
	v_add_u32_e32 v68, v141, v137
	ds_read_b128 v[64:67], v68
	ds_read_b128 v[68:71], v68 offset:4096
	v_add_u32_e32 v140, v141, v138
	ds_read_b128 v[136:139], v140
	ds_read_b128 v[142:145], v140 offset:4096
	v_exp_f32_e32 v194, v80
	v_exp_f32_e32 v195, v81
	v_exp_f32_e32 v218, v82
	v_exp_f32_e32 v219, v83
	v_exp_f32_e32 v220, v84
	v_exp_f32_e32 v221, v85
	v_exp_f32_e32 v222, v86
	v_exp_f32_e32 v223, v87
	v_exp_f32_e32 v224, v88
	v_exp_f32_e32 v225, v89
	v_exp_f32_e32 v226, v90
	v_exp_f32_e32 v227, v91
	v_exp_f32_e32 v228, v92
	v_exp_f32_e32 v229, v93
	v_exp_f32_e32 v230, v94
	v_exp_f32_e32 v231, v95
	v_add_u32_e32 v140, v141, v146
	s_waitcnt vmcnt(0)
	s_mul_hi_u32 s0, s50, 0xaaaaaaab
	s_lshr_b32 s0, s0, 1
	s_mul_i32 s1, s0, 0x6000
	s_mul_i32 s0, s0, 0xc000
	v_subrev_u32_e32 v72, s0, v207
	v_add_u32_e32 v72, v214, v72
	ds_write_b128 v72, v[124:127]
	v_subrev_u32_e32 v72, s0, v206
	v_add_u32_e32 v72, v214, v72
	ds_write_b128 v72, v[128:131]
	v_subrev_u32_e32 v72, s1, v205
	v_add_u32_e32 v72, s13, v72
	ds_write_b128 v72, v[132:135]
	s_waitcnt lgkmcnt(6)
	v_mfma_f32_32x32x16_bf16 v[80:95], v[64:67], v[108:111], v[236:251]
	v_exp_f32_e32 v146, v151
	v_exp_f32_e32 v151, v167
	v_exp_f32_e32 v167, v189
	v_exp_f32_e32 v189, v193
	s_waitcnt lgkmcnt(5)
	v_mfma_f32_32x32x16_bf16 v[64:79], v[68:71], v[108:111], v[236:251]
	s_waitcnt lgkmcnt(4)
	v_mfma_f32_32x32x16_bf16 v[80:95], v[136:139], v[104:107], v[80:95]
	s_waitcnt lgkmcnt(3)
	v_mfma_f32_32x32x16_bf16 v[64:79], v[142:145], v[104:107], v[64:79]
	ds_read_b128 v[136:139], v140
	ds_read_b128 v[142:145], v140 offset:4096
	v_add_u32_e32 v140, v141, v147
	v_exp_f32_e32 v147, v164
	v_exp_f32_e32 v164, v186
	v_exp_f32_e32 v186, v190
	v_exp_f32_e32 v190, v148
	s_waitcnt lgkmcnt(1)
	v_mfma_f32_32x32x16_bf16 v[80:95], v[136:139], v[100:103], v[80:95]
	s_waitcnt lgkmcnt(0)
	v_mfma_f32_32x32x16_bf16 v[64:79], v[142:145], v[100:103], v[64:79]
	ds_read_b128 v[136:139], v140
	ds_read_b128 v[140:143], v140 offset:4096
	v_exp_f32_e32 v144, v149
	v_exp_f32_e32 v145, v150
	v_exp_f32_e32 v149, v165
	v_exp_f32_e32 v150, v166
	v_exp_f32_e32 v165, v187
	v_exp_f32_e32 v166, v188
	s_waitcnt lgkmcnt(1)
	v_mfma_f32_32x32x16_bf16 v[80:95], v[136:139], v[96:99], v[80:95]
	v_add_f32_e32 v136, v195, v194
	v_add_f32_e32 v136, v218, v136
	v_add_f32_e32 v136, v219, v136
	v_add_f32_e32 v136, v220, v136
	v_add_f32_e32 v136, v221, v136
	v_add_f32_e32 v136, v222, v136
	v_add_f32_e32 v136, v223, v136
	v_add_f32_e32 v136, v224, v136
	v_add_f32_e32 v136, v225, v136
	v_add_f32_e32 v136, v226, v136
	v_add_f32_e32 v136, v227, v136
	v_add_f32_e32 v136, v228, v136
	v_add_f32_e32 v136, v229, v136
	v_add_f32_e32 v136, v230, v136
	v_add_f32_e32 v136, v231, v136
	v_add_f32_e32 v136, v144, v136
	v_add_f32_e32 v136, v145, v136
	v_add_f32_e32 v136, v146, v136
	v_add_f32_e32 v136, v147, v136
	v_add_f32_e32 v136, v149, v136
	v_add_f32_e32 v136, v150, v136
	v_add_f32_e32 v136, v151, v136
	v_add_f32_e32 v136, v164, v136
	v_exp_f32_e32 v187, v191
	v_add_f32_e32 v136, v165, v136
	v_exp_f32_e32 v188, v192
	v_add_f32_e32 v136, v166, v136
	s_waitcnt lgkmcnt(0)
	v_mfma_f32_32x32x16_bf16 v[64:79], v[140:143], v[96:99], v[64:79]
	v_add_f32_e32 v136, v167, v136
	v_add_f32_e32 v136, v186, v136
	v_add_f32_e32 v136, v187, v136
	v_add_f32_e32 v136, v188, v136
	v_add_f32_e32 v136, v189, v136
	v_add_f32_e32 v216, v190, v136
	v_mov_b32_e32 v217, v216
	v_cvt_pk_bf16_f32 v136, v194, v195
	v_cvt_pk_bf16_f32 v137, v218, v219
	v_cvt_pk_bf16_f32 v138, v220, v221
	v_cvt_pk_bf16_f32 v139, v222, v223
	v_cvt_pk_bf16_f32 v140, v224, v225
	v_cvt_pk_bf16_f32 v141, v226, v227
	v_cvt_pk_bf16_f32 v142, v228, v229
	v_cvt_pk_bf16_f32 v143, v230, v231
	v_cvt_pk_bf16_f32 v144, v144, v145
	v_cvt_pk_bf16_f32 v145, v146, v147
	v_cvt_pk_bf16_f32 v146, v149, v150
	v_cvt_pk_bf16_f32 v147, v151, v164
	v_cvt_pk_bf16_f32 v148, v165, v166
	v_cvt_pk_bf16_f32 v149, v167, v186
	v_cvt_pk_bf16_f32 v150, v187, v188
	v_cvt_pk_bf16_f32 v151, v189, v190
	s_nop 1
	v_permlane32_swap_b32_e32 v216, v217
	v_permlane32_swap_b32_e32 v136, v138
	v_permlane32_swap_b32_e32 v137, v139
	v_permlane32_swap_b32_e32 v140, v142
	v_permlane32_swap_b32_e32 v141, v143
	v_permlane32_swap_b32_e32 v144, v146
	v_permlane32_swap_b32_e32 v145, v147
	v_permlane32_swap_b32_e32 v148, v150
	v_permlane32_swap_b32_e32 v149, v151
	s_cmp_ge_u32 s45, s44
	s_cselect_b64 s[10:11], -1, 0
	s_and_b64 vcc, exec, s[10:11]
	s_cbranch_vccnz .LBB0_76
	v_add_co_u32_e32 v112, vcc, 0x1a810000, v158
	s_nop 1
	v_addc_co_u32_e32 v113, vcc, 0, v159, vcc
	v_add_co_u32_e32 v114, vcc, 0x1a812000, v158
	s_nop 1
	v_addc_co_u32_e32 v115, vcc, 0, v159, vcc
	v_add_co_u32_e32 v120, vcc, 0x18608000, v160
	global_load_dwordx4 v[116:119], v[112:113], off
	s_nop 0
	global_load_dwordx4 v[112:115], v[114:115], off
	v_addc_co_u32_e32 v121, vcc, 0, v161, vcc
	global_load_dwordx4 v[120:123], v[120:121], off

; #define SBAR() __builtin_amdgcn_sched_barrier(0)
; #define SLOAD(i, k0) do { sr_[i].vs0 = *reinterpret_cast<const bf16x8*>(&Vh[(size_t)((k0) + sr) * 128 + sc]); sr_[i].vs1 = *reinterpret_cast<const bf16x8*>(&Vh[(size_t)((k0) + 32 + sr) * 128 + sc]); \
;     sr_[i].ks0 = *reinterpret_cast<const bf16x8*>(&Kh[(size_t)((k0) + kr) * 64 + kc]); } while (0)
; #define SWRITE(b, i) do { *(bf16x8*)(V_lds + (b) * AT_SHM_V + vst0) = sr_[i].vs0; *(bf16x8*)(V_lds + (b) * AT_SHM_V + vst1) = sr_[i].vs1; \
;     *(bf16x8*)(K_lds + (b) * AT_SHM_K + kst) = sr_[i].ks0; } while (0)
; #define SWAIT() asm volatile("s_waitcnt vmcnt(3)" ::: "memory")
; DEV void partialSM(f32x16& p0, f32x16& p1, float& m_reg, float& mn, float& alpha) {
;     ...
;   for (int r = 0; r < 16; ++r) p0[r] = __builtin_amdgcn_exp2f(p0[r]);
; }
; DEV void finishSM(f32x16& p0, f32x16& p1, float alpha, float& l_reg, bf16x8& pa0, bf16x8& pa1, bf16x8& pa2, bf16x8& pa3) {
; #pragma unroll
;   for (int r = 0; r < 16; ++r) p1[r] = __builtin_amdgcn_exp2f(p1[r]);
;   float ps = 0;
; #pragma unroll
;   for (int r = 0; r < 16; ++r) ps += p0[r];
; #pragma unroll
;   for (int r = 0; r < 16; ++r) ps += p1[r];
;   { auto rr = __builtin_amdgcn_permlane32_swap(__float_as_uint(ps), __float_as_uint(ps), false, false);
;     ps = __uint_as_float(rr[0]) + __uint_as_float(rr[1]); }
;   l_reg = l_reg * alpha + ps;
;     ...
;   PK4(p0, 0, pa0); PK4(p0, 8, pa1); PK4(p1, 0, pa2); PK4(p1, 8, pa3);
; DEV void attn_pass(const u16* __restrict__ Qb, const u16* __restrict__ Kh, const u16* __restrict__ Vh, int seq, f32x16* o, float* rli) {
;     ...
;     SBAR(); qkt(pB0, pB1, K_lds + b0 * AT_SHM_K, qr, r32, hi);
;     finishSM(pA0, pA1, alA, l_reg, pa0, pa1, pa2, pa3); SBAR();
;     SLOAD(SO, (j + 2) * 64); SBAR();
;     pv_d0(o, vb0 + bm1 * AT_SHM_V, pa0, pa1, pa2, pa3); partialSM(pB0, pB1, m_reg, mnB, alB);
;     SWAIT(); SWRITE(b1, SE);
;     RESC(alB); __syncthreads();
;     SBAR(); qkt(pA0, pA1, K_lds + b1 * AT_SHM_K, qr, r32, hi);
;     finishSM(pB0, pB1, alB, l_reg, pa0, pa1, pa2, pa3); SBAR();
;     if (j + 3 < NT) SLOAD(SE, (j + 3) * 64); SBAR();
;     pv_d0(o, vb0 + b0 * AT_SHM_V, pa0, pa1, pa2, pa3); partialSM(pA0, pA1, m_reg, mnA, alA);
.LBB0_94:
	v_subrev_u32_e32 v137, s15, v198
	v_subrev_u32_e32 v138, s15, v200
	v_subrev_u32_e32 v146, s15, v202
	v_subrev_u32_e32 v147, s15, v204
	v_mov_b32_e32 v149, v64
	v_mov_b32_e32 v150, v65
	v_mov_b32_e32 v151, v66
	v_mov_b32_e32 v164, v67
	v_mov_b32_e32 v165, v68
	v_mov_b32_e32 v166, v69
	v_mov_b32_e32 v167, v70
	v_mov_b32_e32 v186, v71
	v_mov_b32_e32 v187, v72
	v_mov_b32_e32 v188, v73
	v_mov_b32_e32 v189, v74
	v_mov_b32_e32 v190, v75
	v_mov_b32_e32 v191, v76
	v_mov_b32_e32 v192, v77
	v_mov_b32_e32 v193, v78
	v_mov_b32_e32 v148, v79
	s_waitcnt lgkmcnt(0)
	s_barrier
	v_add_u32_e32 v68, v141, v137
	ds_read_b128 v[64:67], v68
	ds_read_b128 v[68:71], v68 offset:4096
	v_add_u32_e32 v140, v141, v138
	ds_read_b128 v[136:139], v140
	ds_read_b128 v[142:145], v140 offset:4096
	v_exp_f32_e32 v194, v80
	v_exp_f32_e32 v195, v81
	v_exp_f32_e32 v221, v82
	v_exp_f32_e32 v222, v83
	v_exp_f32_e32 v223, v84
	v_exp_f32_e32 v224, v85
	v_exp_f32_e32 v225, v86
	v_exp_f32_e32 v226, v87
	v_exp_f32_e32 v227, v88
	v_exp_f32_e32 v228, v89
	v_exp_f32_e32 v229, v90
	v_exp_f32_e32 v230, v91
	v_exp_f32_e32 v231, v92
	v_exp_f32_e32 v232, v93
	v_exp_f32_e32 v233, v94
	v_exp_f32_e32 v234, v95
	v_add_u32_e32 v140, v141, v146
	s_waitcnt vmcnt(0)
	s_mul_hi_u32 s0, s64, 0xaaaaaaab
	s_lshr_b32 s0, s0, 1
	s_mul_i32 s1, s0, 0x6000
	s_mul_i32 s0, s0, 0xc000
	v_subrev_u32_e32 v72, s0, v210
	v_add_u32_e32 v72, v217, v72
	ds_write_b128 v72, v[124:127]
	v_subrev_u32_e32 v72, s0, v209
	v_add_u32_e32 v72, v217, v72
	ds_write_b128 v72, v[128:131]
	v_subrev_u32_e32 v72, s1, v208
	v_add_u32_e32 v72, s13, v72
	ds_write_b128 v72, v[132:135]
	s_waitcnt lgkmcnt(6)
	v_mfma_f32_32x32x16_bf16 v[80:95], v[64:67], v[108:111], v[236:251]
	v_exp_f32_e32 v146, v151
	v_exp_f32_e32 v151, v167
	v_exp_f32_e32 v167, v189
	v_exp_f32_e32 v189, v193
	s_waitcnt lgkmcnt(5)
	v_mfma_f32_32x32x16_bf16 v[64:79], v[68:71], v[108:111], v[236:251]
	s_waitcnt lgkmcnt(4)
	v_mfma_f32_32x32x16_bf16 v[80:95], v[136:139], v[104:107], v[80:95]
	s_waitcnt lgkmcnt(3)
	v_mfma_f32_32x32x16_bf16 v[64:79], v[142:145], v[104:107], v[64:79]
	ds_read_b128 v[136:139], v140
	ds_read_b128 v[142:145], v140 offset:4096
	v_add_u32_e32 v140, v141, v147
	v_exp_f32_e32 v147, v164
	v_exp_f32_e32 v164, v186
	v_exp_f32_e32 v186, v190
	v_exp_f32_e32 v190, v148
	s_waitcnt lgkmcnt(1)
	v_mfma_f32_32x32x16_bf16 v[80:95], v[136:139], v[100:103], v[80:95]
	s_waitcnt lgkmcnt(0)
	v_mfma_f32_32x32x16_bf16 v[64:79], v[142:145], v[100:103], v[64:79]
	ds_read_b128 v[136:139], v140
	ds_read_b128 v[140:143], v140 offset:4096
	v_exp_f32_e32 v144, v149
	v_exp_f32_e32 v145, v150
	v_exp_f32_e32 v149, v165
	v_exp_f32_e32 v150, v166
	v_exp_f32_e32 v165, v187
	v_exp_f32_e32 v166, v188
	s_waitcnt lgkmcnt(1)
	v_mfma_f32_32x32x16_bf16 v[80:95], v[136:139], v[96:99], v[80:95]
	v_add_f32_e32 v136, v195, v194
	v_add_f32_e32 v136, v221, v136
	v_add_f32_e32 v136, v222, v136
	v_add_f32_e32 v136, v223, v136
	v_add_f32_e32 v136, v224, v136
	v_add_f32_e32 v136, v225, v136
	v_add_f32_e32 v136, v226, v136
	v_add_f32_e32 v136, v227, v136
	v_add_f32_e32 v136, v228, v136
	v_add_f32_e32 v136, v229, v136
	v_add_f32_e32 v136, v230, v136
	v_add_f32_e32 v136, v231, v136
	v_add_f32_e32 v136, v232, v136
	v_add_f32_e32 v136, v233, v136
	v_add_f32_e32 v136, v234, v136
	v_add_f32_e32 v136, v144, v136
	v_add_f32_e32 v136, v145, v136
	v_add_f32_e32 v136, v146, v136
	v_add_f32_e32 v136, v147, v136
	v_add_f32_e32 v136, v149, v136
	v_add_f32_e32 v136, v150, v136
	v_add_f32_e32 v136, v151, v136
	v_add_f32_e32 v136, v164, v136
	v_exp_f32_e32 v187, v191
	v_add_f32_e32 v136, v165, v136
	v_exp_f32_e32 v188, v192
	v_add_f32_e32 v136, v166, v136
	s_waitcnt lgkmcnt(0)
	v_mfma_f32_32x32x16_bf16 v[64:79], v[140:143], v[96:99], v[64:79]
	v_add_f32_e32 v136, v167, v136
	v_add_f32_e32 v136, v186, v136
	v_add_f32_e32 v136, v187, v136
	v_add_f32_e32 v136, v188, v136
	v_add_f32_e32 v136, v189, v136
	v_add_f32_e32 v219, v190, v136
	v_mov_b32_e32 v220, v219
	v_cvt_pk_bf16_f32 v136, v194, v195
	v_cvt_pk_bf16_f32 v137, v221, v222
	v_cvt_pk_bf16_f32 v138, v223, v224
	v_cvt_pk_bf16_f32 v139, v225, v226
	v_cvt_pk_bf16_f32 v140, v227, v228
	v_cvt_pk_bf16_f32 v141, v229, v230
	v_cvt_pk_bf16_f32 v142, v231, v232
	v_cvt_pk_bf16_f32 v143, v233, v234
	v_cvt_pk_bf16_f32 v144, v144, v145
	v_cvt_pk_bf16_f32 v145, v146, v147
	v_cvt_pk_bf16_f32 v146, v149, v150
	v_cvt_pk_bf16_f32 v147, v151, v164
	v_cvt_pk_bf16_f32 v148, v165, v166
	v_cvt_pk_bf16_f32 v149, v167, v186
	v_cvt_pk_bf16_f32 v150, v187, v188
	v_cvt_pk_bf16_f32 v151, v189, v190
	s_nop 1
	v_permlane32_swap_b32_e32 v219, v220
	v_permlane32_swap_b32_e32 v136, v138
	v_permlane32_swap_b32_e32 v137, v139
	v_permlane32_swap_b32_e32 v140, v142
	v_permlane32_swap_b32_e32 v141, v143
	v_permlane32_swap_b32_e32 v144, v146
	v_permlane32_swap_b32_e32 v145, v147
	v_permlane32_swap_b32_e32 v148, v150
	v_permlane32_swap_b32_e32 v149, v151
	s_cmp_ge_u32 s48, s44
	s_cselect_b64 s[10:11], -1, 0
	s_and_b64 vcc, exec, s[10:11]
	s_cbranch_vccnz .LBB0_96
	v_add_co_u32_e32 v112, vcc, 0x1a810000, v168
	s_nop 1
	v_addc_co_u32_e32 v113, vcc, 0, v169, vcc
	v_add_co_u32_e32 v114, vcc, 0x1a812000, v168
	s_nop 1
	v_addc_co_u32_e32 v115, vcc, 0, v169, vcc
	v_add_co_u32_e32 v120, vcc, 0x18690000, v170
	global_load_dwordx4 v[116:119], v[112:113], off
	s_nop 0
	global_load_dwordx4 v[112:115], v[114:115], off
	v_addc_co_u32_e32 v121, vcc, 0, v171, vcc
	global_load_dwordx4 v[120:123], v[120:121], off
